# grid barrier: member workgroups watch the top-level arrival counter (>= (gen+1)*nx) instead of a generation word: released when the last XCD leader's increment lands, no wait for its returned value +
# baseline (speedup 1.0000x reference)
; DI unsigned xb_ld(unsigned* p) { return __hip_atomic_load(p, __ATOMIC_RELAXED, __HIP_MEMORY_SCOPE_AGENT); }
; DI unsigned xb_add(unsigned* p, unsigned v) { return __hip_atomic_fetch_add(p, v, __ATOMIC_RELAXED, __HIP_MEMORY_SCOPE_AGENT); }
; #define XB_SPIN(cond, bar) do { unsigned _sp = 0; while (cond) { __builtin_amdgcn_s_sleep(1); \
;     if ((++_sp & 255u) == 0u) { if (xb_ld(&(bar)[XB_TMO])) break; if (_sp > XB_SPIN_CAP) { atomicAdd(&(bar)[XB_TMO], 1u); break; } } } } while (0)
; DI void xcd_barrier(const XcdBarrier& b) {
;     ...
;     const unsigned old = xb_add(&bar[XB_XSUB(b.x)], 1u);
;     const unsigned gen = old / nloc;
;     if (old + 1u == (gen + 1u) * nloc) {
;       __builtin_amdgcn_fence(__ATOMIC_RELEASE, "agent");
;       asm volatile("s_waitcnt vmcnt(0)" ::: "memory");
;       const unsigned og = xb_add(&bar[XB_TOP], 1u);
;       const unsigned tg = og / nx;
;       if (og + 1u == (tg + 1u) * nx) xb_add(&bar[XB_TOPGEN], 1u);
;       else XB_SPIN(xb_ld(&bar[XB_TOPGEN]) == tg, bar);
;       __builtin_amdgcn_fence(__ATOMIC_ACQUIRE, "agent");
;       xb_add(&bar[XB_XGEN(b.x)], 1u);
;       asm volatile("s_waitcnt vmcnt(0)" ::: "memory");
;     } else {
;       XB_SPIN(xb_ld(&bar[XB_XGEN(b.x)]) == gen, bar);
;       __builtin_amdgcn_fence(__ATOMIC_ACQUIRE, "agent");
.LBB0_279:
	s_or_b64 exec, exec, s[14:15]
	v_cvt_f32_u32_e32 v6, v4
	s_waitcnt vmcnt(0)
	v_readfirstlane_b32 s2, v5
	v_sub_u32_e32 v5, 0, v4
	v_rcp_iflag_f32_e32 v6, v6
	v_add_u32_e32 v7, s2, v3
	v_mul_f32_e32 v6, 0x4f7ffffe, v6
	v_cvt_u32_f32_e32 v6, v6
	v_mul_lo_u32 v3, v5, v6
	v_mul_hi_u32 v3, v6, v3
	v_add_u32_e32 v3, v6, v3
	v_mul_hi_u32 v3, v7, v3
	v_mul_lo_u32 v5, v3, v4
	v_sub_u32_e32 v5, v7, v5
	v_add_u32_e32 v6, 1, v3
	v_cmp_ge_u32_e32 vcc, v5, v4
	s_nop 1
	v_cndmask_b32_e32 v3, v3, v6, vcc
	v_sub_u32_e32 v6, v5, v4
	v_cndmask_b32_e32 v5, v5, v6, vcc
	v_add_u32_e32 v6, 1, v3
	v_cmp_ge_u32_e32 vcc, v5, v4
	v_add_u32_e32 v5, 1, v7
	s_nop 0
	v_cndmask_b32_e32 v3, v3, v6, vcc
	v_mul_lo_u32 v6, v4, v3
	v_add_u32_e32 v4, v6, v4
	v_cmp_ne_u32_e32 vcc, v5, v4
	s_and_saveexec_b64 s[2:3], vcc
	s_xor_b64 s[12:13], exec, s[2:3]
	s_cbranch_execz .LBB0_293
	s_waitcnt lgkmcnt(0)
	buffer_inv sc1
	v_mad_u32_u24 v6, v3, v2, v2
	s_add_u32 s22, s8, 0xfc9f400
	s_addc_u32 s23, s9, 0
	global_load_dword v2, v199, s[22:23] sc1
	s_waitcnt vmcnt(0)
	v_cmp_lt_u32_e32 vcc, v2, v6
	s_and_saveexec_b64 s[14:15], vcc
	s_cbranch_execz .LBB0_292
	s_add_u32 s18, s8, 0xfc9c200
	s_addc_u32 s19, s9, 0
	s_mov_b32 s2, 1
	s_mov_b64 s[24:25], 0
	s_branch .LBB0_283

; DI unsigned xb_ld(unsigned* p) { return __hip_atomic_load(p, __ATOMIC_RELAXED, __HIP_MEMORY_SCOPE_AGENT); }
; #define XB_SPIN(cond, bar) do { unsigned _sp = 0; while (cond) { __builtin_amdgcn_s_sleep(1); \
;     if ((++_sp & 255u) == 0u) { if (xb_ld(&(bar)[XB_TMO])) break; if (_sp > XB_SPIN_CAP) { atomicAdd(&(bar)[XB_TMO], 1u); break; } } } } while (0)
; DI void xcd_barrier(const XcdBarrier& b) {
;     ...
;       XB_SPIN(xb_ld(&bar[XB_XGEN(b.x)]) == gen, bar);
.LBB0_285:
	global_load_dword v2, v199, s[22:23] sc1
	s_add_i32 s2, s2, 1
	s_mov_b64 s[34:35], -1
	s_waitcnt vmcnt(0)
	v_cmp_ge_u32_e32 vcc, v2, v6
	s_orn2_b64 s[28:29], vcc, exec
	s_branch .LBB0_282

; DI unsigned xb_ld(unsigned* p) { return __hip_atomic_load(p, __ATOMIC_RELAXED, __HIP_MEMORY_SCOPE_AGENT); }
; DI unsigned xb_add(unsigned* p, unsigned v) { return __hip_atomic_fetch_add(p, v, __ATOMIC_RELAXED, __HIP_MEMORY_SCOPE_AGENT); }
; #define XB_SPIN(cond, bar) do { unsigned _sp = 0; while (cond) { __builtin_amdgcn_s_sleep(1); \
;     if ((++_sp & 255u) == 0u) { if (xb_ld(&(bar)[XB_TMO])) break; if (_sp > XB_SPIN_CAP) { atomicAdd(&(bar)[XB_TMO], 1u); break; } } } } while (0)
; DI void xcd_barrier(const XcdBarrier& b) {
;     ...
;     const unsigned old = xb_add(&bar[XB_XSUB(b.x)], 1u);
;     const unsigned gen = old / nloc;
;     if (old + 1u == (gen + 1u) * nloc) {
;       __builtin_amdgcn_fence(__ATOMIC_RELEASE, "agent");
;       asm volatile("s_waitcnt vmcnt(0)" ::: "memory");
;       const unsigned og = xb_add(&bar[XB_TOP], 1u);
;       const unsigned tg = og / nx;
;       if (og + 1u == (tg + 1u) * nx) xb_add(&bar[XB_TOPGEN], 1u);
;       else XB_SPIN(xb_ld(&bar[XB_TOPGEN]) == tg, bar);
;       __builtin_amdgcn_fence(__ATOMIC_ACQUIRE, "agent");
;       xb_add(&bar[XB_XGEN(b.x)], 1u);
;       asm volatile("s_waitcnt vmcnt(0)" ::: "memory");
;     } else {
;       XB_SPIN(xb_ld(&bar[XB_XGEN(b.x)]) == gen, bar);
;       __builtin_amdgcn_fence(__ATOMIC_ACQUIRE, "agent");
.LBB0_875:
	s_or_b64 exec, exec, s[14:15]
	v_cvt_f32_u32_e32 v6, v4
	s_waitcnt vmcnt(0)
	v_readfirstlane_b32 s2, v5
	v_sub_u32_e32 v5, 0, v4
	v_rcp_iflag_f32_e32 v6, v6
	v_add_u32_e32 v7, s2, v3
	v_mul_f32_e32 v6, 0x4f7ffffe, v6
	v_cvt_u32_f32_e32 v6, v6
	v_mul_lo_u32 v3, v5, v6
	v_mul_hi_u32 v3, v6, v3
	v_add_u32_e32 v3, v6, v3
	v_mul_hi_u32 v3, v7, v3
	v_mul_lo_u32 v5, v3, v4
	v_sub_u32_e32 v5, v7, v5
	v_add_u32_e32 v6, 1, v3
	v_cmp_ge_u32_e32 vcc, v5, v4
	s_nop 1
	v_cndmask_b32_e32 v3, v3, v6, vcc
	v_sub_u32_e32 v6, v5, v4
	v_cndmask_b32_e32 v5, v5, v6, vcc
	v_add_u32_e32 v6, 1, v3
	v_cmp_ge_u32_e32 vcc, v5, v4
	v_add_u32_e32 v5, 1, v7
	s_nop 0
	v_cndmask_b32_e32 v3, v3, v6, vcc
	v_mul_lo_u32 v6, v4, v3
	v_add_u32_e32 v4, v6, v4
	v_cmp_ne_u32_e32 vcc, v5, v4
	s_and_saveexec_b64 s[2:3], vcc
	s_xor_b64 s[12:13], exec, s[2:3]
	s_cbranch_execz .LBB0_889
	s_waitcnt lgkmcnt(0)
	buffer_inv sc1
	v_mad_u32_u24 v6, v3, v2, v2
	s_add_u32 s18, s8, 0xfc9f400
	s_addc_u32 s19, s9, 0
	global_load_dword v2, v199, s[18:19] sc1
	s_waitcnt vmcnt(0)
	v_cmp_lt_u32_e32 vcc, v2, v6
	s_and_saveexec_b64 s[14:15], vcc
	s_cbranch_execz .LBB0_888
	s_add_u32 s16, s8, 0xfc9c200
	s_addc_u32 s17, s9, 0
	s_mov_b32 s2, 1
	s_mov_b64 s[22:23], 0
	s_branch .LBB0_879

; DI unsigned xb_ld(unsigned* p) { return __hip_atomic_load(p, __ATOMIC_RELAXED, __HIP_MEMORY_SCOPE_AGENT); }
; #define XB_SPIN(cond, bar) do { unsigned _sp = 0; while (cond) { __builtin_amdgcn_s_sleep(1); \
;     if ((++_sp & 255u) == 0u) { if (xb_ld(&(bar)[XB_TMO])) break; if (_sp > XB_SPIN_CAP) { atomicAdd(&(bar)[XB_TMO], 1u); break; } } } } while (0)
; DI void xcd_barrier(const XcdBarrier& b) {
;     ...
;       XB_SPIN(xb_ld(&bar[XB_XGEN(b.x)]) == gen, bar);
.LBB0_881:
	global_load_dword v2, v199, s[18:19] sc1
	s_add_i32 s2, s2, 1
	s_mov_b64 s[28:29], -1
	s_waitcnt vmcnt(0)
	v_cmp_ge_u32_e32 vcc, v2, v6
	s_orn2_b64 s[26:27], vcc, exec
	s_branch .LBB0_878

; DI unsigned xb_ld(unsigned* p) { return __hip_atomic_load(p, __ATOMIC_RELAXED, __HIP_MEMORY_SCOPE_AGENT); }
; DI unsigned xb_add(unsigned* p, unsigned v) { return __hip_atomic_fetch_add(p, v, __ATOMIC_RELAXED, __HIP_MEMORY_SCOPE_AGENT); }
; #define XB_SPIN(cond, bar) do { unsigned _sp = 0; while (cond) { __builtin_amdgcn_s_sleep(1); \
;     if ((++_sp & 255u) == 0u) { if (xb_ld(&(bar)[XB_TMO])) break; if (_sp > XB_SPIN_CAP) { atomicAdd(&(bar)[XB_TMO], 1u); break; } } } } while (0)
; DI void xcd_barrier(const XcdBarrier& b) {
;     ...
;     const unsigned old = xb_add(&bar[XB_XSUB(b.x)], 1u);
;     const unsigned gen = old / nloc;
;     if (old + 1u == (gen + 1u) * nloc) {
;       __builtin_amdgcn_fence(__ATOMIC_RELEASE, "agent");
;       asm volatile("s_waitcnt vmcnt(0)" ::: "memory");
;       const unsigned og = xb_add(&bar[XB_TOP], 1u);
;       const unsigned tg = og / nx;
;       if (og + 1u == (tg + 1u) * nx) xb_add(&bar[XB_TOPGEN], 1u);
;       else XB_SPIN(xb_ld(&bar[XB_TOPGEN]) == tg, bar);
;       __builtin_amdgcn_fence(__ATOMIC_ACQUIRE, "agent");
;       xb_add(&bar[XB_XGEN(b.x)], 1u);
;       asm volatile("s_waitcnt vmcnt(0)" ::: "memory");
;     } else {
;       XB_SPIN(xb_ld(&bar[XB_XGEN(b.x)]) == gen, bar);
;       __builtin_amdgcn_fence(__ATOMIC_ACQUIRE, "agent");
.LBB0_1819:
	s_or_b64 exec, exec, s[18:19]
	v_cvt_f32_u32_e32 v6, v4
	s_waitcnt vmcnt(0)
	v_readfirstlane_b32 s2, v5
	v_sub_u32_e32 v5, 0, v4
	v_rcp_iflag_f32_e32 v6, v6
	v_add_u32_e32 v7, s2, v3
	v_mul_f32_e32 v6, 0x4f7ffffe, v6
	v_cvt_u32_f32_e32 v6, v6
	v_mul_lo_u32 v3, v5, v6
	v_mul_hi_u32 v3, v6, v3
	v_add_u32_e32 v3, v6, v3
	v_mul_hi_u32 v3, v7, v3
	v_mul_lo_u32 v5, v3, v4
	v_sub_u32_e32 v5, v7, v5
	v_add_u32_e32 v6, 1, v3
	v_cmp_ge_u32_e32 vcc, v5, v4
	s_nop 1
	v_cndmask_b32_e32 v3, v3, v6, vcc
	v_sub_u32_e32 v6, v5, v4
	v_cndmask_b32_e32 v5, v5, v6, vcc
	v_add_u32_e32 v6, 1, v3
	v_cmp_ge_u32_e32 vcc, v5, v4
	v_add_u32_e32 v5, 1, v7
	s_nop 0
	v_cndmask_b32_e32 v3, v3, v6, vcc
	v_mul_lo_u32 v6, v4, v3
	v_add_u32_e32 v4, v6, v4
	v_cmp_ne_u32_e32 vcc, v5, v4
	s_and_saveexec_b64 s[2:3], vcc
	s_xor_b64 s[16:17], exec, s[2:3]
	s_cbranch_execz .LBB0_1833
	s_waitcnt lgkmcnt(0)
	buffer_inv sc1
	v_mad_u32_u24 v6, v3, v2, v2
	s_add_u32 s24, s12, 0xfc9f400
	s_addc_u32 s25, s13, 0
	global_load_dword v2, v199, s[24:25] sc1
	s_waitcnt vmcnt(0)
	v_cmp_lt_u32_e32 vcc, v2, v6
	s_and_saveexec_b64 s[18:19], vcc
	s_cbranch_execz .LBB0_1832
	s_add_u32 s22, s12, 0xfc9c200
	s_addc_u32 s23, s13, 0
	s_mov_b32 s2, 1
	s_mov_b64 s[26:27], 0
	s_branch .LBB0_1823

; DI unsigned xb_ld(unsigned* p) { return __hip_atomic_load(p, __ATOMIC_RELAXED, __HIP_MEMORY_SCOPE_AGENT); }
; #define XB_SPIN(cond, bar) do { unsigned _sp = 0; while (cond) { __builtin_amdgcn_s_sleep(1); \
;     if ((++_sp & 255u) == 0u) { if (xb_ld(&(bar)[XB_TMO])) break; if (_sp > XB_SPIN_CAP) { atomicAdd(&(bar)[XB_TMO], 1u); break; } } } } while (0)
; DI void xcd_barrier(const XcdBarrier& b) {
;     ...
;       XB_SPIN(xb_ld(&bar[XB_XGEN(b.x)]) == gen, bar);
.LBB0_1825:
	global_load_dword v2, v199, s[24:25] sc1
	s_add_i32 s2, s2, 1
	s_mov_b64 s[36:37], -1
	s_waitcnt vmcnt(0)
	v_cmp_ge_u32_e32 vcc, v2, v6
	s_orn2_b64 s[34:35], vcc, exec
	s_branch .LBB0_1822
